# P2 phase: rope-key rotation job done by workgroups 192..255 only (they own one GEMM tile less in that phase)
# baseline (speedup 1.0000x reference)
; DI bf16_t f2bf(float x) { unsigned u = __float_as_uint(x); u += 0x7fffu + ((u >> 16) & 1u); return (bf16_t)(u >> 16); }
; DI float bf2f(bf16_t b) { return __uint_as_float(((unsigned)b) << 16); }
;     DI bf16_t* z() const { return (bf16_t*)(ws + WS_Z); }
;     DI bf16_t* kr() const { return (bf16_t*)(ws + WS_KR); }
;     DI float* rope() const { return (float*)(ws + WS_ROPE); }
; DI void job_krope(Frame& F) {
;     for (int i = blockIdx.x * NT + F.tid; i < M * 16; i += gridDim.x * NT) {
;         const int row = i >> 4, j = i & 15, t = row & (S - 1);
;         const float c = F.rope()[t * 16 + j], s = F.rope()[S * 16 + t * 16 + j];
;         const float x1 = bf2f(F.z()[(size_t)row * ZP + Z_KR + j]), x2 = bf2f(F.z()[(size_t)row * ZP + Z_KR + 16 + j]);
;         F.kr()[(size_t)row * 32 + j] = f2bf(x1 * c - x2 * s); F.kr()[(size_t)row * 32 + 16 + j] = f2bf(x2 * c + x1 * s);
;     }
; }
.LBB0_1624:
	s_sub_i32 s8, s2, 192
	s_lshl_b32 s8, s8, 9
	s_cmp_lt_u32 s2, 192
	s_cselect_b32 s8, 0x40000, s8
	v_add_u32_e32 v6, s8, v232
	s_mov_b32 s8, 0x40000
	v_cmp_gt_i32_e32 vcc, s8, v6
	s_and_saveexec_b64 s[10:11], vcc
	s_cbranch_execz .LBB0_1627
	v_and_b32_e32 v0, 15, v232
	v_lshlrev_b32_e32 v0, 1, v0
	s_waitcnt lgkmcnt(0)
	v_lshl_add_u64 v[2:3], s[76:77], 0, v[0:1]
	s_mov_b64 s[8:9], 0xf100000
	v_lshl_add_u64 v[2:3], v[2:3], 0, s[8:9]
	v_readlane_b32 s8, v254, 44
	s_add_u32 s42, s76, 0xf600000
	v_readlane_b32 s9, v254, 45
	s_addc_u32 s43, s77, 0
	s_nop 0
	v_lshl_add_u64 v[4:5], s[8:9], 0, v[0:1]
	s_mov_b64 s[8:9], 0
.LBB0_1626:
	v_lshlrev_b32_sdwa v0, v227, v6 dst_sel:DWORD dst_unused:UNUSED_PAD src0_sel:DWORD src1_sel:WORD_0
	v_lshl_add_u64 v[10:11], s[42:43], 0, v[0:1]
	v_ashrrev_i32_e32 v8, 4, v6
	v_add_co_u32_e32 v10, vcc, 0x40000, v10
	v_ashrrev_i32_e32 v9, 31, v8
	s_nop 0
	v_addc_co_u32_e32 v11, vcc, 0, v11, vcc
	global_load_dword v0, v0, s[42:43]
	v_add_u32_e32 v6, 0x8000, v6
	global_load_dword v7, v[10:11], off
	v_lshlrev_b64 v[10:11], 12, v[8:9]
	v_lshl_add_u64 v[10:11], v[4:5], 0, v[10:11]
	global_load_ushort v12, v[10:11], off offset:768
	s_mov_b32 s16, 0x3ffff
	global_load_ushort v10, v[10:11], off offset:800
	v_lshlrev_b64 v[8:9], 6, v[8:9]
	v_cmp_lt_i32_e32 vcc, s16, v6
	v_lshl_add_u64 v[8:9], v[2:3], 0, v[8:9]
	s_or_b64 s[8:9], vcc, s[8:9]
	s_waitcnt vmcnt(1)
	v_lshlrev_b32_e32 v12, 16, v12
	s_waitcnt vmcnt(0)
	v_lshlrev_b32_e32 v10, 16, v10
	v_mul_f32_e32 v11, v7, v10
	v_fma_f32 v11, v0, v12, -v11
	v_mul_f32_e32 v0, v0, v10
	v_fmac_f32_e32 v0, v7, v12
	v_bfe_u32 v13, v11, 16, 1
	v_bfe_u32 v7, v0, 16, 1
	v_add3_u32 v11, v11, v13, s12
	v_add3_u32 v0, v0, v7, s12
	global_store_short_d16_hi v[8:9], v11, off
	global_store_short_d16_hi v[8:9], v0, off offset:32
	s_andn2_b64 exec, exec, s[8:9]
	s_cbranch_execnz .LBB0_1626
